# P0 rows loop: next-row x prefetch
# speedup vs baseline: 1.0049x; 1.0049x over previous
; #define LAS __attribute__((address_space(3)))
; __device__ __forceinline__ float wave_sum(float v) { for (int o = 32; o >= 1; o >>= 1) v += __shfl_xor(v, o); return v; }
; __device__ __forceinline__ void wave_lds_sync() { asm volatile("s_waitcnt lgkmcnt(0)" ::: "memory"); __builtin_amdgcn_wave_barrier(); }
; __device__ __forceinline__ u32x2 pk4(f32x4 v) { u32x2 w; w.x = cvt_pk_bf16(v[0], v[1]); w.y = cvt_pk_bf16(v[2], v[3]); return w; }
; __device__ __forceinline__ void p0_rows(const Args& a, LAS unsigned char* lds, int gw, int NGW, int wave, int lane, int tid) {
;     ...
;     const f32x4* gp = (const f32x4*)a.in[I_NMPRE] + lane; f32x4 g[4];
; #pragma unroll
;     for (int j = 0; j < 4; ++j) g[j] = gp[64 * j];
;     for (int row = gw; row < MT; row += NGW) {
;         const f32x4* xr = (const f32x4*)xrow_ptr(a, row) + lane; f32x4 v[4]; float s = 0.f;
; #pragma unroll
;         for (int j = 0; j < 4; ++j) { v[j] = xr[64 * j]; s += (v[j][0] * v[j][0] + v[j][1] * v[j][1]) + (v[j][2] * v[j][2] + v[j][3] * v[j][3]); }
;         const float rstd = rsqrtf(wave_sum(s) * (1.f / DM) + EPS);
;         u32x2* ho = (u32x2*)(H + (size_t)row * DM) + lane;
; #pragma unroll
;         for (int j = 0; j < 4; ++j) { v[j] = v[j] * rstd * g[j]; ho[64 * j] = pk4(v[j]); *(LAS f32x4*)(hrow + j * 264 + 4 * lane) = v[j]; }
;         wave_lds_sync();
;         const int jj = lane & 15, p = lane >> 4; float acc = 0.f;
;         const LAS float* hp = hrow + p * 264; const LAS float* wp = WdL + p * 4112 + jj;
.LBB0_137:
	s_or_b64 exec, exec, s[0:1]
	s_cmpk_lt_i32 s81, 0x4400
	s_waitcnt lgkmcnt(0)
	s_barrier
	s_cbranch_scc0 .LBB0_144
	v_readlane_b32 s36, v252, 1
	v_lshlrev_b32_e32 v30, 4, v176
	v_readlane_b32 s46, v252, 11
	v_readlane_b32 s47, v252, 12
	s_nop 4
	global_load_dwordx4 v[0:3], v30, s[46:47]
	global_load_dwordx4 v[4:7], v30, s[46:47] offset:1024
	global_load_dwordx4 v[8:11], v30, s[46:47] offset:2048
	global_load_dwordx4 v[12:15], v30, s[46:47] offset:3072
	v_mbcnt_lo_u32_b32 v21, -1, 0
	v_mbcnt_hi_u32_b32 v26, -1, v21
	v_and_b32_e32 v21, 64, v26
	v_add_u32_e32 v27, 64, v21
	v_xor_b32_e32 v21, 32, v26
	v_cmp_lt_i32_e32 vcc, v21, v27
	v_xor_b32_e32 v22, 16, v26
	v_xor_b32_e32 v23, 8, v26
	v_cndmask_b32_e32 v21, v26, v21, vcc
	v_cmp_lt_i32_e32 vcc, v22, v27
	v_mov_b32_e32 v19, 0
	v_lshlrev_b32_e32 v18, 3, v176
	v_cndmask_b32_e32 v22, v26, v22, vcc
	v_cmp_lt_i32_e32 vcc, v23, v27
	v_xor_b32_e32 v24, 4, v26
	v_lshl_add_u64 v[16:17], s[52:53], 0, v[18:19]
	v_lshlrev_b32_e32 v18, 2, v176
	v_cndmask_b32_e32 v23, v26, v23, vcc
	v_cmp_lt_i32_e32 vcc, v24, v27
	v_xor_b32_e32 v25, 2, v26
	v_lshl_add_u64 v[18:19], s[52:53], 0, v[18:19]
	s_mov_b64 s[0:1], 0x4000000
	v_cndmask_b32_e32 v24, v26, v24, vcc
	v_cmp_lt_i32_e32 vcc, v25, v27
	v_xor_b32_e32 v28, 1, v26
	v_lshl_add_u64 v[18:19], v[18:19], 0, s[0:1]
	s_mul_i32 s0, s93, 0x1080
	v_cndmask_b32_e32 v25, v26, v25, vcc
	v_cmp_lt_i32_e32 vcc, v28, v27
	v_lshrrev_b32_e32 v27, 4, v176
	s_add_i32 s1, s0, 0
	v_cndmask_b32_e32 v26, v26, v28, vcc
	v_mul_u32_u24_e32 v28, 0x4040, v27
	s_add_i32 s1, s1, 0x10100
	v_lshl_or_b32 v20, v20, 2, v28
	s_movk_i32 s3, 0x420
	v_mov_b32_e32 v28, s0
	v_lshlrev_b32_e32 v21, 2, v21
	v_lshlrev_b32_e32 v22, 2, v22
	v_lshlrev_b32_e32 v23, 2, v23
	v_lshlrev_b32_e32 v24, 2, v24
	v_lshlrev_b32_e32 v25, 2, v25
	v_lshlrev_b32_e32 v26, 2, v26
	v_cmp_gt_u32_e32 vcc, 16, v176
	v_mad_u32_u24 v27, v27, s3, v28
	v_lshlrev_b32_e32 v28, 4, v176
	v_mov_b32_e32 v29, 0x358637bd
	s_mov_b32 s3, 0x800000
	v_add_u32_e32 v30, s1, v30
	s_mov_b32 s6, s81
	v_readlane_b32 s37, v252, 2
	v_readlane_b32 s38, v252, 3
	v_readlane_b32 s39, v252, 4
	v_readlane_b32 s40, v252, 5
	v_readlane_b32 s41, v252, 6
	v_readlane_b32 s42, v252, 7
	v_readlane_b32 s43, v252, 8
	v_readlane_b32 s44, v252, 9
	v_readlane_b32 s45, v252, 10
	v_readlane_b32 s48, v252, 13
	v_readlane_b32 s49, v252, 14
	v_readlane_b32 s50, v252, 15
	v_readlane_b32 s51, v252, 16
	v_readlane_b32 s36, v252, 1
	v_readlane_b32 s37, v252, 2
	v_readlane_b32 s38, v252, 3
	v_readlane_b32 s39, v252, 4
	s_nop 3
	s_add_i32 s100, s6, 0xffffc000
	s_ashr_i32 s99, s6, 31
	s_cmpk_lt_i32 s6, 0x4000
	s_cselect_b32 s101, s99, 0
	s_cselect_b32 s100, s6, s100
	s_cselect_b32 s99, s37, s39
	s_cselect_b32 s98, s36, s38
	s_lshl_b64 s[100:101], s[100:101], 12
	s_add_u32 s98, s98, s100
	s_addc_u32 s99, s99, s101
	global_load_dwordx4 v[80:83], v28, s[98:99]
	global_load_dwordx4 v[84:87], v28, s[98:99] offset:1024
	global_load_dwordx4 v[88:91], v28, s[98:99] offset:3072
	global_load_dwordx4 v[92:95], v28, s[98:99] offset:2048
	s_waitcnt vmcnt(0)
	s_branch .Lrows_body

; #define LAS __attribute__((address_space(3)))
; __device__ __forceinline__ float wave_sum(float v) { for (int o = 32; o >= 1; o >>= 1) v += __shfl_xor(v, o); return v; }
; __device__ __forceinline__ void wave_lds_sync() { asm volatile("s_waitcnt lgkmcnt(0)" ::: "memory"); __builtin_amdgcn_wave_barrier(); }
; __device__ __forceinline__ u32x2 pk4(f32x4 v) { u32x2 w; w.x = cvt_pk_bf16(v[0], v[1]); w.y = cvt_pk_bf16(v[2], v[3]); return w; }
; __device__ __forceinline__ void p0_rows(const Args& a, LAS unsigned char* lds, int gw, int NGW, int wave, int lane, int tid) {
;     ...
;     for (int row = gw; row < MT; row += NGW) {
;         const f32x4* xr = (const f32x4*)xrow_ptr(a, row) + lane; f32x4 v[4]; float s = 0.f;
; #pragma unroll
;         for (int j = 0; j < 4; ++j) { v[j] = xr[64 * j]; s += (v[j][0] * v[j][0] + v[j][1] * v[j][1]) + (v[j][2] * v[j][2] + v[j][3] * v[j][3]); }
;         const float rstd = rsqrtf(wave_sum(s) * (1.f / DM) + EPS);
;         u32x2* ho = (u32x2*)(H + (size_t)row * DM) + lane;
; #pragma unroll
;         for (int j = 0; j < 4; ++j) { v[j] = v[j] * rstd * g[j]; ho[64 * j] = pk4(v[j]); *(LAS f32x4*)(hrow + j * 264 + 4 * lane) = v[j]; }
;         wave_lds_sync();
.LBB0_140:
	s_waitcnt vmcnt(1)
.Lrows_body:
	v_mov_b64_e32 v[32:33], v[80:81]
	v_mov_b64_e32 v[34:35], v[82:83]
	v_mov_b64_e32 v[36:37], v[84:85]
	v_mov_b64_e32 v[38:39], v[86:87]
	v_mov_b64_e32 v[40:41], v[88:89]
	v_mov_b64_e32 v[42:43], v[90:91]
	v_mov_b64_e32 v[44:45], v[92:93]
	v_mov_b64_e32 v[46:47], v[94:95]
	s_ashr_i32 s7, s6, 31
	s_add_i32 s98, s6, s96
	s_cmpk_gt_i32 s98, 0x43ff
	s_cbranch_scc1 .Lrows_nopf
	v_readlane_b32 s36, v252, 1
	v_readlane_b32 s37, v252, 2
	v_readlane_b32 s38, v252, 3
	v_readlane_b32 s39, v252, 4
	s_nop 3
	s_add_i32 s100, s98, 0xffffc000
	s_ashr_i32 s99, s98, 31
	s_cmpk_lt_i32 s98, 0x4000
	s_cselect_b32 s101, s99, 0
	s_cselect_b32 s100, s98, s100
	s_cselect_b32 s99, s37, s39
	s_cselect_b32 s98, s36, s38
	s_lshl_b64 s[100:101], s[100:101], 12
	s_add_u32 s98, s98, s100
	s_addc_u32 s99, s99, s101
	global_load_dwordx4 v[80:83], v28, s[98:99]
	global_load_dwordx4 v[84:87], v28, s[98:99] offset:1024
	global_load_dwordx4 v[88:91], v28, s[98:99] offset:3072
	global_load_dwordx4 v[92:95], v28, s[98:99] offset:2048
.Lrows_nopf:
	s_lshl_b64 s[8:9], s[6:7], 11
	v_readlane_b32 s40, v252, 5
	v_readlane_b32 s41, v252, 6
	v_readlane_b32 s42, v252, 7
	v_readlane_b32 s43, v252, 8
	v_readlane_b32 s44, v252, 9
	v_readlane_b32 s45, v252, 10
	v_readlane_b32 s46, v252, 11
	v_readlane_b32 s47, v252, 12
	v_readlane_b32 s48, v252, 13
	v_readlane_b32 s49, v252, 14
	v_readlane_b32 s50, v252, 15
	v_readlane_b32 s51, v252, 16
	v_pk_mul_f32 v[48:49], v[34:35], v[34:35]
	v_pk_mul_f32 v[50:51], v[32:33], v[32:33]
	v_pk_mul_f32 v[52:53], v[38:39], v[38:39]
	v_pk_mul_f32 v[54:55], v[36:37], v[36:37]
	v_pk_mov_b32 v[60:61], v[50:51], v[48:49] op_sel:[1,0]
	v_mov_b32_e32 v51, v49
	v_pk_mov_b32 v[48:49], v[54:55], v[52:53] op_sel:[1,0]
	v_mov_b32_e32 v55, v53
	v_mul_f32_e32 v59, v41, v41
	v_mul_f32_e32 v56, v45, v45
	v_mul_f32_e32 v58, v47, v47
	v_pk_add_f32 v[50:51], v[60:61], v[50:51]
	v_pk_add_f32 v[48:49], v[48:49], v[54:55]
	v_mul_f32_e32 v31, v40, v40
	v_mul_f32_e32 v62, v42, v42
	v_mul_f32_e32 v63, v43, v43
	v_pk_fma_f32 v[52:53], v[44:45], v[44:45], v[56:57] op_sel_hi:[1,1,0]
	v_pk_fma_f32 v[56:57], v[46:47], v[46:47], v[58:59] op_sel_hi:[1,1,0]
	v_pk_add_f32 v[50:51], v[50:51], v[50:51] op_sel:[0,1] op_sel_hi:[1,0]
	v_pk_add_f32 v[48:49], v[48:49], v[48:49] op_sel:[0,1] op_sel_hi:[1,0]
	v_mov_b32_e32 v53, v62
	v_mov_b32_e32 v57, v63
	v_mov_b32_e32 v51, v31
	v_mov_b32_e32 v49, v59
	v_pk_add_f32 v[52:53], v[52:53], v[56:57]
	v_pk_add_f32 v[48:49], v[50:51], v[48:49]
	s_nop 0
	v_pk_add_f32 v[48:49], v[48:49], v[52:53]
	s_nop 0
	v_add_f32_e32 v31, v48, v49
	ds_bpermute_b32 v48, v21, v31
	s_waitcnt lgkmcnt(0)
	v_add_f32_e32 v31, v31, v48
	ds_bpermute_b32 v48, v22, v31
	s_waitcnt lgkmcnt(0)
	v_add_f32_e32 v31, v31, v48
	ds_bpermute_b32 v48, v23, v31
	s_waitcnt lgkmcnt(0)
	v_add_f32_e32 v31, v31, v48
	ds_bpermute_b32 v48, v24, v31
	s_waitcnt lgkmcnt(0)
	v_add_f32_e32 v31, v31, v48
	ds_bpermute_b32 v48, v25, v31
	s_waitcnt lgkmcnt(0)
	v_add_f32_e32 v31, v31, v48
	ds_bpermute_b32 v48, v26, v31
	s_waitcnt lgkmcnt(0)
	v_add_f32_e32 v31, v31, v48
	v_fmamk_f32 v31, v31, 0x3a800000, v29
	v_mul_f32_e32 v48, 0x4b800000, v31
	v_cmp_gt_f32_e64 s[0:1], s3, v31
	s_nop 1
	v_cndmask_b32_e64 v31, v31, v48, s[0:1]
	v_rsq_f32_e32 v31, v31
	v_lshl_add_u64 v[48:49], v[16:17], 0, s[8:9]
	v_mul_f32_e32 v50, 0x45800000, v31
	v_cndmask_b32_e64 v50, v31, v50, s[0:1]
	v_pk_mul_f32 v[32:33], v[32:33], v[50:51] op_sel_hi:[1,0]
	v_pk_mul_f32 v[34:35], v[34:35], v[50:51] op_sel_hi:[1,0]
	v_pk_mul_f32 v[36:37], v[36:37], v[50:51] op_sel_hi:[1,0]
	v_pk_mul_f32 v[38:39], v[38:39], v[50:51] op_sel_hi:[1,0]
	v_pk_mul_f32 v[44:45], v[44:45], v[50:51] op_sel_hi:[1,0]
	v_pk_mul_f32 v[46:47], v[46:47], v[50:51] op_sel_hi:[1,0]
	v_pk_mul_f32 v[52:53], v[40:41], v[50:51] op_sel_hi:[1,0]
	v_pk_mul_f32 v[50:51], v[42:43], v[50:51] op_sel_hi:[1,0]
	v_pk_mul_f32 v[34:35], v[2:3], v[34:35]
	v_pk_mul_f32 v[32:33], v[0:1], v[32:33]
	v_pk_mul_f32 v[38:39], v[6:7], v[38:39]
	v_pk_mul_f32 v[36:37], v[4:5], v[36:37]
	v_pk_mul_f32 v[42:43], v[10:11], v[46:47]
	v_pk_mul_f32 v[40:41], v[8:9], v[44:45]
	v_pk_mul_f32 v[46:47], v[14:15], v[50:51]
	v_pk_mul_f32 v[44:45], v[12:13], v[52:53]
	v_cvt_pk_bf16_f32 v50, v32, v33
	v_cvt_pk_bf16_f32 v51, v34, v35
	ds_write_b128 v30, v[32:35]
	v_cvt_pk_bf16_f32 v32, v36, v37
	v_cvt_pk_bf16_f32 v33, v38, v39
	ds_write_b128 v30, v[36:39] offset:1056
	v_cvt_pk_bf16_f32 v34, v40, v41
	v_cvt_pk_bf16_f32 v35, v42, v43
	ds_write_b128 v30, v[40:43] offset:2112
	v_cvt_pk_bf16_f32 v36, v44, v45
	v_cvt_pk_bf16_f32 v37, v46, v47
	ds_write_b128 v30, v[44:47] offset:3168
	global_store_dwordx2 v[48:49], v[50:51], off
	global_store_dwordx2 v[48:49], v[32:33], off offset:512
	global_store_dwordx2 v[48:49], v[34:35], off offset:1024
	global_store_dwordx2 v[48:49], v[36:37], off offset:1536
	s_waitcnt lgkmcnt(0)
	s_movk_i32 s0, 0x100
	v_mov_b32_e32 v31, v27
	v_mov_b32_e32 v33, v20
	v_mov_b32_e32 v32, 0

; __global__ void __launch_bounds__(512) fwd_kernel(Args a) {
	.amdhsa_kernel _Z10fwd_kernel4Args
		.amdhsa_group_segment_fixed_size 0
		.amdhsa_private_segment_fixed_size 0
		.amdhsa_kernarg_size 440
		.amdhsa_user_sgpr_count 2
		.amdhsa_user_sgpr_dispatch_ptr 0
		.amdhsa_user_sgpr_queue_ptr 0
		.amdhsa_user_sgpr_kernarg_segment_ptr 1
		.amdhsa_user_sgpr_dispatch_id 0
		.amdhsa_user_sgpr_kernarg_preload_length 0
		.amdhsa_user_sgpr_kernarg_preload_offset 0
		.amdhsa_user_sgpr_private_segment_size 0
		.amdhsa_uses_dynamic_stack 0
		.amdhsa_enable_private_segment 0
		.amdhsa_system_sgpr_workgroup_id_x 1
		.amdhsa_system_sgpr_workgroup_id_y 0
		.amdhsa_system_sgpr_workgroup_id_z 0
		.amdhsa_system_sgpr_workgroup_info 0
		.amdhsa_system_vgpr_workitem_id 2
		.amdhsa_next_free_vgpr 256
		.amdhsa_next_free_sgpr 102
		.amdhsa_accum_offset 256
		.amdhsa_reserve_vcc 1
		.amdhsa_float_round_mode_32 0
		.amdhsa_float_round_mode_16_64 0
		.amdhsa_float_denorm_mode_32 3
		.amdhsa_float_denorm_mode_16_64 3
		.amdhsa_dx10_clamp 1
		.amdhsa_ieee_mode 1
		.amdhsa_fp16_overflow 0
		.amdhsa_tg_split 0
		.amdhsa_exception_fp_ieee_invalid_op 0
		.amdhsa_exception_fp_denorm_src 0
		.amdhsa_exception_fp_ieee_div_zero 0
		.amdhsa_exception_fp_ieee_overflow 0
		.amdhsa_exception_fp_ieee_underflow 0
		.amdhsa_exception_fp_ieee_inexact 0
		.amdhsa_exception_int_div_zero 0
	.end_amdhsa_kernel

; __global__ void __launch_bounds__(512) fwd_kernel(Args a) {
amdhsa.kernels:
  - .agpr_count:     0
    .args:
      - .offset:         0
        .size:           184
        .value_kind:     by_value
      - .offset:         184
        .size:           4
        .value_kind:     hidden_block_count_x
      - .offset:         188
        .size:           4
        .value_kind:     hidden_block_count_y
      - .offset:         192
        .size:           4
        .value_kind:     hidden_block_count_z
      - .offset:         196
        .size:           2
        .value_kind:     hidden_group_size_x
      - .offset:         198
        .size:           2
        .value_kind:     hidden_group_size_y
      - .offset:         200
        .size:           2
        .value_kind:     hidden_group_size_z
      - .offset:         202
        .size:           2
        .value_kind:     hidden_remainder_x
      - .offset:         204
        .size:           2
        .value_kind:     hidden_remainder_y
      - .offset:         206
        .size:           2
        .value_kind:     hidden_remainder_z
      - .offset:         224
        .size:           8
        .value_kind:     hidden_global_offset_x
      - .offset:         232
        .size:           8
        .value_kind:     hidden_global_offset_y
      - .offset:         240
        .size:           8
        .value_kind:     hidden_global_offset_z
      - .offset:         248
        .size:           2
        .value_kind:     hidden_grid_dims
      - .offset:         272
        .size:           8
        .value_kind:     hidden_multigrid_sync_arg
      - .offset:         304
        .size:           4
        .value_kind:     hidden_dynamic_lds_size
    .group_segment_fixed_size: 0
    .kernarg_segment_align: 8
    .kernarg_segment_size: 440
    .language:       OpenCL C
    .language_version:
      - 2
      - 0
    .max_flat_workgroup_size: 512
    .name:           _Z10fwd_kernel4Args
    .private_segment_fixed_size: 0
    .sgpr_count:     108
    .sgpr_spill_count: 19
    .symbol:         _Z10fwd_kernel4Args.kd
    .uniform_work_group_size: 1
    .uses_dynamic_stack: false
    .vgpr_count:     256
    .vgpr_spill_count: 0
    .wavefront_size: 64
